# plus P6 Hyena pre-pass loop software-pipelined: next block image + conv weights requested during the current block's convolution
# speedup vs baseline: 1.0042x; 1.0042x over previous
.LBB0_1966:
	s_or_b64 exec, exec, s[8:9]
	s_andn2_b64 vcc, exec, s[52:53]
	s_mov_b32 s8, s96
	s_cbranch_vccnz .LBB0_1970
	s_ashr_i32 s9, s8, 31
	s_lshl_b64 s[16:17], s[8:9], 15
	s_add_u32 s16, s67, s16
	s_addc_u32 s17, s68, s17
	v_lshl_add_u64 v[64:65], s[16:17], 0, v[122:123]
	global_load_dwordx4 v[48:51], v[64:65], off
	global_load_dwordx4 v[52:55], v[64:65], off offset:32
	global_load_dwordx4 v[56:59], v[64:65], off offset:16
	global_load_dwordx4 v[60:63], v[64:65], off offset:48
	s_lshr_b32 s16, s8, 4
	s_lshl_b32 s16, s16, 3
	s_add_i32 s16, s16, s88
	s_lshl_b32 s16, s16, 2
	s_add_u32 s18, s44, s16
	s_addc_u32 s19, s45, 0
	s_add_u32 s20, s46, s16
	s_addc_u32 s21, s47, 0
	global_load_dword v40, v147, s[18:19]
	global_load_dword v41, v4, s[20:21]
	global_load_dword v42, v4, s[18:19]
	global_load_dword v43, v146, s[18:19] offset:2048
	s_waitcnt vmcnt(0)
.LBB0_1967:
	s_ashr_i32 s9, s8, 31
	s_lshl_b64 s[10:11], s[8:9], 15
	s_waitcnt lgkmcnt(0)
	s_barrier
	s_mov_b32 s9, 0
	s_waitcnt vmcnt(16)
	v_mov_b32_e32 v66, v41
	v_mov_b32_e32 v67, v41
	v_mov_b32_e32 v68, v42
	v_mov_b32_e32 v69, v42
	v_mov_b32_e32 v70, v43
	v_mov_b32_e32 v71, v43
	v_mov_b32_e32 v72, v40
	v_mov_b32_e32 v73, v40
	v_and_b32_e32 v2, 0xffff, v48
	v_and_b32_e32 v3, 0xffff, v52
	v_lshrrev_b32_e32 v5, 16, v48
	v_lshrrev_b32_e32 v10, 16, v52
	v_and_b32_e32 v22, 0xffff, v49
	v_lshrrev_b32_e32 v24, 16, v49
	v_and_b32_e32 v23, 0xffff, v53
	v_lshrrev_b32_e32 v11, 16, v53
	v_and_b32_e32 v25, 0xffff, v50
	v_and_b32_e32 v26, 0xffff, v54
	v_lshrrev_b32_e32 v27, 16, v50
	v_lshrrev_b32_e32 v28, 16, v54
	v_and_b32_e32 v29, 0xffff, v51
	v_and_b32_e32 v30, 0xffff, v55
	v_lshrrev_b32_e32 v31, 16, v51
	v_lshrrev_b32_e32 v32, 16, v55
	v_lshl_or_b32 v2, v56, 16, v2
	v_lshl_or_b32 v3, v60, 16, v3
	v_and_or_b32 v6, v56, s76, v5
	v_and_or_b32 v7, v60, s76, v10
	v_lshl_or_b32 v8, v57, 16, v22
	v_and_or_b32 v10, v57, s76, v24
	v_lshl_or_b32 v9, v61, 16, v23
	v_and_or_b32 v11, v61, s76, v11
	v_lshl_or_b32 v12, v58, 16, v25
	v_lshl_or_b32 v13, v62, 16, v26
	v_and_or_b32 v14, v58, s76, v27
	v_and_or_b32 v15, v62, s76, v28
	v_lshl_or_b32 v18, v59, 16, v29
	v_lshl_or_b32 v19, v63, 16, v30
	v_and_or_b32 v16, v59, s76, v31
	v_and_or_b32 v17, v63, s76, v32
	ds_write_b64 v145, v[2:3] offset:8
	ds_write_b64 v145, v[6:7] offset:4136
	ds_write_b64 v145, v[8:9] offset:8264
	ds_write_b64 v145, v[10:11] offset:12392
	ds_write_b64 v145, v[12:13] offset:16520
	ds_write_b64 v145, v[14:15] offset:20648
	ds_write_b64 v145, v[18:19] offset:24776
	ds_write_b64 v145, v[16:17] offset:28904
	s_add_i32 s16, s8, s22
	s_cmpk_gt_i32 s16, 0xbff
	s_cbranch_scc1 .Lpp_nopf
	s_ashr_i32 s17, s16, 31
	s_lshl_b64 s[18:19], s[16:17], 15
	s_add_u32 s18, s67, s18
	s_addc_u32 s19, s68, s19
	v_lshl_add_u64 v[64:65], s[18:19], 0, v[122:123]
	global_load_dwordx4 v[48:51], v[64:65], off
	global_load_dwordx4 v[52:55], v[64:65], off offset:32
	global_load_dwordx4 v[56:59], v[64:65], off offset:16
	global_load_dwordx4 v[60:63], v[64:65], off offset:48
	s_lshr_b32 s16, s16, 4
	s_lshl_b32 s16, s16, 3
	s_add_i32 s16, s16, s88
	s_lshl_b32 s16, s16, 2
	s_add_u32 s18, s44, s16
	s_addc_u32 s19, s45, 0
	s_add_u32 s20, s46, s16
	s_addc_u32 s21, s47, 0
	global_load_dword v40, v147, s[18:19]
	global_load_dword v41, v4, s[20:21]
	global_load_dword v42, v4, s[18:19]
	global_load_dword v43, v146, s[18:19] offset:2048
.Lpp_nopf:
	s_waitcnt lgkmcnt(0)
	s_barrier
	v_lshl_add_u64 v[12:13], v[124:125], 0, s[10:11]
.LBB0_1968:
	v_add_u32_e32 v5, s9, v144
	ds_read2_b32 v[14:15], v5 offset1:1
	ds_read2_b32 v[16:17], v5 offset0:1 offset1:2
	ds_read2_b32 v[18:19], v5 offset0:64 offset1:65
	ds_read2_b32 v[20:21], v5 offset0:65 offset1:66
	ds_read2_b32 v[22:23], v5 offset0:128 offset1:129
	ds_read2_b32 v[24:25], v5 offset0:129 offset1:130
	ds_read2_b32 v[26:27], v5 offset0:192 offset1:193
	ds_read2_b32 v[28:29], v5 offset0:193 offset1:194
	s_waitcnt lgkmcnt(7)
	v_and_b32_e32 v14, 0xffff0000, v14
	v_lshlrev_b32_e32 v15, 16, v15
	s_waitcnt lgkmcnt(6)
	v_and_b32_e32 v31, 16, v17
	v_and_b32_e32 v30, 0xffff0000, v16
	s_waitcnt lgkmcnt(5)
	v_and_b32_e32 v18, 0xffff0000, v18
	v_lshlrev_b32_e32 v19, 16, v19
	s_waitcnt lgkmcnt(4)
	v_and_b32_e32 v33, 16, v21
	v_and_b32_e32 v32, 0xffff0000, v20
	s_waitcnt lgkmcnt(3)
	v_and_b32_e32 v22, 0xffff0000, v22
	v_lshlrev_b32_e32 v23, 16, v23
	s_waitcnt lgkmcnt(2)
	v_and_b32_e32 v35, 16, v25
	v_and_b32_e32 v34, 0xffff0000, v24
	s_waitcnt lgkmcnt(1)
	v_and_b32_e32 v26, 0xffff0000, v26
	v_lshlrev_b32_e32 v27, 16, v27
	s_waitcnt lgkmcnt(0)
	v_and_b32_e32 v37, 16, v29
	v_and_b32_e32 v36, 0xffff0000, v28
	v_mov_b32_e32 v16, v30
	v_pk_mov_b32 v[30:31], v[14:15], v[30:31] op_sel:[1,0]
	v_pk_fma_f32 v[14:15], v[68:69], v[14:15], v[66:67]
	v_lshlrev_b32_e32 v17, 16, v17
	v_mov_b32_e32 v20, v32
	v_pk_mov_b32 v[32:33], v[18:19], v[32:33] op_sel:[1,0]
	v_pk_fma_f32 v[18:19], v[68:69], v[18:19], v[66:67]
	v_mov_b32_e32 v24, v34
	v_pk_mov_b32 v[34:35], v[22:23], v[34:35] op_sel:[1,0]
	v_pk_fma_f32 v[22:23], v[68:69], v[22:23], v[66:67]
	v_mov_b32_e32 v28, v36
	v_pk_mov_b32 v[36:37], v[26:27], v[36:37] op_sel:[1,0]
	v_pk_fma_f32 v[26:27], v[68:69], v[26:27], v[66:67]
	v_pk_fma_f32 v[14:15], v[70:71], v[30:31], v[14:15]
	v_lshlrev_b32_e32 v21, 16, v21
	v_lshlrev_b32_e32 v25, 16, v25
	v_lshlrev_b32_e32 v29, 16, v29
	v_pk_fma_f32 v[18:19], v[70:71], v[32:33], v[18:19]
	v_pk_fma_f32 v[22:23], v[70:71], v[34:35], v[22:23]
	v_pk_fma_f32 v[26:27], v[70:71], v[36:37], v[26:27]
	v_pk_fma_f32 v[14:15], v[72:73], v[16:17], v[14:15]
	s_addk_i32 s9, 0x400
	s_mov_b64 s[10:11], 0x400
	v_pk_fma_f32 v[16:17], v[72:73], v[20:21], v[18:19]
	v_pk_fma_f32 v[18:19], v[72:73], v[24:25], v[22:23]
	v_pk_fma_f32 v[20:21], v[72:73], v[28:29], v[26:27]
	v_cvt_pk_bf16_f32 v5, v14, v15
	s_cmpk_eq_i32 s9, 0x1000
	v_cvt_pk_bf16_f32 v14, v16, v17
	v_cvt_pk_bf16_f32 v15, v18, v19
	v_cvt_pk_bf16_f32 v16, v20, v21
	global_store_dword v[12:13], v5, off offset:-512
	global_store_dword v[12:13], v14, off offset:-256
	global_store_dword v[12:13], v15, off
	global_store_dword v[12:13], v16, off offset:256
	v_lshl_add_u64 v[12:13], v[12:13], 0, s[10:11]
	s_cbranch_scc0 .LBB0_1968
	s_add_i32 s8, s8, s22
	s_cmpk_gt_i32 s8, 0xbff
	s_cbranch_scc0 .LBB0_1967
